# scan compute path: odd lanes hold row pair swapped so d and y cross-lane sums need one register (36 instr slots per step instead of 39)
# speedup vs baseline: 1.0653x; 1.0004x over previous
; __device__ __forceinline__ void phase_scan(CParams& p, LAS unsigned char* lds) {
;     ...
;             const int j = lane & 7, row = hf * 32 + wid * 8 + (lane >> 3);
;             f32x2 S[4];
; #pragma unroll
;             for (int i = 0; i < 4; ++i) S[i] = (f32x2){0.f, 0.f};
;             if (!prompt) { const float* sp = p.in[I_SWKV] + ((size_t)chain * 64 + row) * 64; const f32x4 a = *(const f32x4*)(sp + 4 * j), bq = *(const f32x4*)(sp + 32 + 4 * j);
;                 S[0] = a.lo; S[1] = a.hi; S[2] = bq.lo; S[3] = bq.hi; }
.LBB0_137:
	s_ashr_i32 s12, s1, 1
	s_and_b32 s33, s1, 1
	s_and_b64 s[2:3], s[50:51], exec
	s_cselect_b32 s1, 16, 0x1000
	s_add_i32 s2, s1, 31
	s_lshr_b32 s3, s2, 5
	s_mov_b64 s[54:55], -1
	s_and_b64 vcc, exec, s[4:5]
	s_cbranch_vccz .LBB0_147
	v_and_b32_e32 v112, 63, v192
	v_lshrrev_b32_e32 v113, 6, v192
	v_and_b32_e32 v114, 15, v112
	v_lshrrev_b32_e32 v115, 4, v112
	v_lshlrev_b32_e32 v116, 3, v113
	v_lshl_add_u32 v116, v115, 1, v116
	v_lshlrev_b32_e32 v100, 4, v114
	s_lshl_b32 s13, s33, 5
	v_add_u32_e32 v103, s13, v116
	v_lshlrev_b32_e32 v101, 2, v103
	v_add_u32_e32 v101, 0x500, v101
	v_lshlrev_b32_e32 v103, 8, v103
	v_add_u32_e32 v103, v103, v100
	v_and_b32_e32 v117, 1, v112
	v_add_u32_e32 v102, v116, v117
	v_lshrrev_b32_e32 v114, 1, v114
	v_lshl_add_u32 v102, v102, 3, v114
	v_lshlrev_b32_e32 v102, 2, v102
	v_add_u32_e32 v102, 0x18600, v102
	v_cmp_eq_u32_e32 vcc, 1, v117
	v_lshlrev_b32_e32 v114, 7, v117
	v_lshrrev_b32_e32 v115, 1, v112
	v_mul_u32_u24_e32 v115, 0x600, v115
	v_lshl_add_u32 v115, v117, 4, v115
	v_lshl_add_u32 v115, v113, 5, v115
	s_lshl_b32 s13, s33, 7
	v_add_u32_e32 v115, s13, v115
	v_add_u32_e32 v118, 0x500, v115
	v_xor_b32_e32 v119, 0x80, v118
	s_mov_b32 s13, 0
	s_lshl_b64 s[54:55], s[12:13], 14
	s_cmp_eq_u64 s[50:51], 0
	s_cbranch_scc1 .Lsc_zero
	s_add_u32 s54, s18, s54
	s_addc_u32 s55, s19, s55
	s_nop 4
	global_load_dwordx4 v[104:107], v103, s[54:55]
	global_load_dwordx4 v[108:111], v103, s[54:55] offset:256
	s_waitcnt vmcnt(0)
	v_cndmask_b32_e32 v32, v104, v108, vcc
	v_cndmask_b32_e32 v33, v108, v104, vcc
	v_cndmask_b32_e32 v34, v105, v109, vcc
	v_cndmask_b32_e32 v35, v109, v105, vcc
	v_cndmask_b32_e32 v36, v106, v110, vcc
	v_cndmask_b32_e32 v37, v110, v106, vcc
	v_cndmask_b32_e32 v38, v107, v111, vcc
	v_cndmask_b32_e32 v39, v111, v107, vcc
	s_branch .Lsc_go

; #define LAS __attribute__((address_space(3)))
; __device__ __forceinline__ float reduce8(float x) { x += dppf<0xB1>(x); x += dppf<0x4E>(x); x += dppf<0x141>(x); return x; }
; __device__ __forceinline__ void phase_scan(CParams& p, LAS unsigned char* lds) {
;     ...
;             for (int c = 0; c < nch; ++c) {
;                 const LAS float* base = (const LAS float*)(lds + (c & 1) * SBUF) + 4 * j;
;                 const LAS float* vb = (const LAS float*)(lds + (c & 1) * SBUF) + 320 + row;
;                 const int nst = (T - c * SCH) < SCH ? (T - c * SCH) : SCH;
;                 ScanOps cur, nxt;
;                 scan_ld(cur, base, vb);
;                 for (int g16 = 0; g16 < nst; g16 += 16) {
;                     unsigned ywb = (unsigned)(YP_OFF + (g16 >> 4) * YP_BYTES + (wid * 64 + lane) * 4);
;                     asm volatile("" : "+v"(ywb));
;                     LAS float* yw = (LAS float*)(lds + ywb);
; #pragma unroll
;                     for (int s16 = 0; s16 < 16; ++s16) {
;                         scan_ld(nxt, base + (g16 + s16 + 1) * 384, vb + (g16 + s16 + 1) * 384);
;                         f32x2 d = S[0] * cur.n0.lo; d = S[1] * cur.n0.hi + d; d = S[2] * cur.n1.lo + d; d = S[3] * cur.n1.hi + d;
;                         const float sa = reduce8(d.x + d.y);
;                         const f32x2 sa2 = (f32x2){sa, sa}, v2 = (f32x2){cur.v, cur.v};
;                         S[0] = S[0] * cur.w0.lo + (cur.b0.lo * sa2 + cur.k0.lo * v2);
;                         S[1] = S[1] * cur.w0.hi + (cur.b0.hi * sa2 + cur.k0.hi * v2);
;                         S[2] = S[2] * cur.w1.lo + (cur.b1.lo * sa2 + cur.k1.lo * v2);
;                         S[3] = S[3] * cur.w1.hi + (cur.b1.hi * sa2 + cur.k1.hi * v2);
;                         f32x2 e = S[0] * cur.r0.lo; e = S[1] * cur.r0.hi + e; e = S[2] * cur.r1.lo + e; e = S[3] * cur.r1.hi + e;
;                         yw[s16 * 256] = e.x + e.y;
;                         cur = nxt;
;                     }
.Lsc_chunk:
	s_lshl_b32 s15, s13, 5
	s_sub_i32 s54, s1, s15
	s_min_i32 s54, s54, 32
	s_bitcmp1_b32 s13, 0
	s_cselect_b32 s55, 0xc000, 0
	v_add_u32_e32 v97, s55, v100
	v_add_u32_e32 v98, s55, v101
	v_mov_b32_e32 v99, v102
	s_mov_b32 s15, 0
	v_add_u32_e32 v120, s55, v118
	v_add_u32_e32 v121, s55, v119
	ds_read_b128 v[40:43], v97 offset:768
	ds_read_b128 v[44:47], v97 offset:1024
	ds_read_b64 v[56:57], v98 offset:0
	ds_read_b128 v[48:51], v97 offset:512
	ds_read_b128 v[52:55], v97 offset:256
	ds_read_b128 v[60:63], v97 offset:0
.Lsc_grp:
	ds_read_b128 v[64:67], v97 offset:2304
	s_waitcnt lgkmcnt(2)
	v_pk_mul_f32 v[84:85], v[32:33], v[40:41] op_sel_hi:[1,0]
	ds_read_b128 v[68:71], v97 offset:2560
	v_pk_fma_f32 v[84:85], v[34:35], v[40:41], v[84:85] op_sel:[0,1,0] op_sel_hi:[1,1,1]
	ds_read_b64 v[58:59], v98 offset:1536
	v_pk_fma_f32 v[84:85], v[36:37], v[42:43], v[84:85] op_sel_hi:[1,0,1]
	ds_read_b128 v[72:75], v97 offset:2048
	v_pk_fma_f32 v[84:85], v[38:39], v[42:43], v[84:85] op_sel:[0,1,0] op_sel_hi:[1,1,1]
	ds_read_b128 v[76:79], v97 offset:1792
	s_nop 0
	v_cndmask_b32_e32 v122, v56, v57, vcc
	v_cndmask_b32_e32 v123, v57, v56, vcc
	v_add_f32_dpp v84, v85, v84 quad_perm:[1,0,3,2] row_mask:0xf bank_mask:0xf bound_ctrl:1
	s_nop 0
	v_pk_mul_f32 v[86:87], v[122:123], v[48:49] op_sel_hi:[1,0]
	v_add_f32_dpp v84, v84, v84 quad_perm:[2,3,0,1] row_mask:0xf bank_mask:0xf bound_ctrl:1
	s_nop 0
	v_pk_mul_f32 v[88:89], v[122:123], v[48:49] op_sel:[0,1] op_sel_hi:[1,1]
	v_add_f32_dpp v84, v84, v84 row_ror:4 row_mask:0xf bank_mask:0xf bound_ctrl:1
	s_nop 0
	v_pk_mul_f32 v[90:91], v[122:123], v[50:51] op_sel_hi:[1,0]
	v_add_f32_dpp v84, v84, v84 row_ror:8 row_mask:0xf bank_mask:0xf bound_ctrl:1
	v_pk_mul_f32 v[92:93], v[122:123], v[50:51] op_sel:[0,1] op_sel_hi:[1,1]
	s_nop 0
	ds_read_b128 v[80:83], v97 offset:1536
	v_mov_b32_dpp v85, v84 quad_perm:[1,0,3,2] row_mask:0xf bank_mask:0xf
	s_nop 0
	v_pk_fma_f32 v[86:87], v[84:85], v[44:45], v[86:87] op_sel_hi:[1,0,1]
	v_pk_fma_f32 v[88:89], v[84:85], v[44:45], v[88:89] op_sel:[0,1,0] op_sel_hi:[1,1,1]
	v_pk_fma_f32 v[90:91], v[84:85], v[46:47], v[90:91] op_sel_hi:[1,0,1]
	v_pk_fma_f32 v[92:93], v[84:85], v[46:47], v[92:93] op_sel:[0,1,0] op_sel_hi:[1,1,1]
	v_pk_fma_f32 v[32:33], v[32:33], v[52:53], v[86:87] op_sel_hi:[1,0,1]
	v_pk_fma_f32 v[34:35], v[34:35], v[52:53], v[88:89] op_sel:[0,1,0] op_sel_hi:[1,1,1]
	v_pk_fma_f32 v[36:37], v[36:37], v[54:55], v[90:91] op_sel_hi:[1,0,1]
	v_pk_fma_f32 v[38:39], v[38:39], v[54:55], v[92:93] op_sel:[0,1,0] op_sel_hi:[1,1,1]
	ds_read_b128 v[40:43], v97 offset:3840
	s_waitcnt lgkmcnt(2)
	v_pk_mul_f32 v[84:85], v[32:33], v[64:65] op_sel_hi:[1,0]
	ds_read_b128 v[44:47], v97 offset:4096
	v_pk_fma_f32 v[84:85], v[34:35], v[64:65], v[84:85] op_sel:[0,1,0] op_sel_hi:[1,1,1]
	ds_read_b64 v[56:57], v98 offset:3072
	v_pk_fma_f32 v[84:85], v[36:37], v[66:67], v[84:85] op_sel_hi:[1,0,1]
	ds_read_b128 v[48:51], v97 offset:3584
	v_pk_fma_f32 v[84:85], v[38:39], v[66:67], v[84:85] op_sel:[0,1,0] op_sel_hi:[1,1,1]
	ds_read_b128 v[52:55], v97 offset:3328
	v_pk_mul_f32 v[94:95], v[32:33], v[60:61] op_sel_hi:[1,0]
	v_cndmask_b32_e32 v122, v58, v59, vcc
	v_cndmask_b32_e32 v123, v59, v58, vcc
	v_add_f32_dpp v84, v85, v84 quad_perm:[1,0,3,2] row_mask:0xf bank_mask:0xf bound_ctrl:1
	v_pk_fma_f32 v[94:95], v[34:35], v[60:61], v[94:95] op_sel:[0,1,0] op_sel_hi:[1,1,1]
	v_pk_mul_f32 v[86:87], v[122:123], v[72:73] op_sel_hi:[1,0]
	v_add_f32_dpp v84, v84, v84 quad_perm:[2,3,0,1] row_mask:0xf bank_mask:0xf bound_ctrl:1
	v_pk_fma_f32 v[94:95], v[36:37], v[62:63], v[94:95] op_sel_hi:[1,0,1]
	v_pk_mul_f32 v[88:89], v[122:123], v[72:73] op_sel:[0,1] op_sel_hi:[1,1]
	v_add_f32_dpp v84, v84, v84 row_ror:4 row_mask:0xf bank_mask:0xf bound_ctrl:1
	v_pk_fma_f32 v[94:95], v[38:39], v[62:63], v[94:95] op_sel:[0,1,0] op_sel_hi:[1,1,1]
	v_pk_mul_f32 v[90:91], v[122:123], v[74:75] op_sel_hi:[1,0]
	v_add_f32_dpp v84, v84, v84 row_ror:8 row_mask:0xf bank_mask:0xf bound_ctrl:1
	v_pk_mul_f32 v[92:93], v[122:123], v[74:75] op_sel:[0,1] op_sel_hi:[1,1]
	v_add_f32_dpp v96, v95, v94 quad_perm:[1,0,3,2] row_mask:0xf bank_mask:0xf bound_ctrl:1
	ds_read_b128 v[60:63], v97 offset:3072
	v_mov_b32_dpp v85, v84 quad_perm:[1,0,3,2] row_mask:0xf bank_mask:0xf
	ds_write_b32 v99, v96 offset:0
	v_pk_fma_f32 v[86:87], v[84:85], v[68:69], v[86:87] op_sel_hi:[1,0,1]
	v_pk_fma_f32 v[88:89], v[84:85], v[68:69], v[88:89] op_sel:[0,1,0] op_sel_hi:[1,1,1]
	v_pk_fma_f32 v[90:91], v[84:85], v[70:71], v[90:91] op_sel_hi:[1,0,1]
	v_pk_fma_f32 v[92:93], v[84:85], v[70:71], v[92:93] op_sel:[0,1,0] op_sel_hi:[1,1,1]
	v_pk_fma_f32 v[32:33], v[32:33], v[76:77], v[86:87] op_sel_hi:[1,0,1]
	v_pk_fma_f32 v[34:35], v[34:35], v[76:77], v[88:89] op_sel:[0,1,0] op_sel_hi:[1,1,1]
	v_pk_fma_f32 v[36:37], v[36:37], v[78:79], v[90:91] op_sel_hi:[1,0,1]
	v_pk_fma_f32 v[38:39], v[38:39], v[78:79], v[92:93] op_sel:[0,1,0] op_sel_hi:[1,1,1]
	ds_read_b128 v[64:67], v97 offset:5376
	s_waitcnt lgkmcnt(3)
; #define LAS __attribute__((address_space(3)))
; __device__ __forceinline__ float reduce8(float x) { x += dppf<0xB1>(x); x += dppf<0x4E>(x); x += dppf<0x141>(x); return x; }
; __device__ __forceinline__ void phase_scan(CParams& p, LAS unsigned char* lds) {
;     ...
;             for (int c = 0; c < nch; ++c) {
;                 const LAS float* base = (const LAS float*)(lds + (c & 1) * SBUF) + 4 * j;
;                 const LAS float* vb = (const LAS float*)(lds + (c & 1) * SBUF) + 320 + row;
;                 const int nst = (T - c * SCH) < SCH ? (T - c * SCH) : SCH;
;                 ScanOps cur, nxt;
;                 scan_ld(cur, base, vb);
;                 for (int g16 = 0; g16 < nst; g16 += 16) {
;                     unsigned ywb = (unsigned)(YP_OFF + (g16 >> 4) * YP_BYTES + (wid * 64 + lane) * 4);
;                     asm volatile("" : "+v"(ywb));
;                     LAS float* yw = (LAS float*)(lds + ywb);
; #pragma unroll
;                     for (int s16 = 0; s16 < 16; ++s16) {
;                         scan_ld(nxt, base + (g16 + s16 + 1) * 384, vb + (g16 + s16 + 1) * 384);
;                         f32x2 d = S[0] * cur.n0.lo; d = S[1] * cur.n0.hi + d; d = S[2] * cur.n1.lo + d; d = S[3] * cur.n1.hi + d;
;                         const float sa = reduce8(d.x + d.y);
;                         const f32x2 sa2 = (f32x2){sa, sa}, v2 = (f32x2){cur.v, cur.v};
;                         S[0] = S[0] * cur.w0.lo + (cur.b0.lo * sa2 + cur.k0.lo * v2);
;                         S[1] = S[1] * cur.w0.hi + (cur.b0.hi * sa2 + cur.k0.hi * v2);
;                         S[2] = S[2] * cur.w1.lo + (cur.b1.lo * sa2 + cur.k1.lo * v2);
;                         S[3] = S[3] * cur.w1.hi + (cur.b1.hi * sa2 + cur.k1.hi * v2);
;                         f32x2 e = S[0] * cur.r0.lo; e = S[1] * cur.r0.hi + e; e = S[2] * cur.r1.lo + e; e = S[3] * cur.r1.hi + e;
;                         yw[s16 * 256] = e.x + e.y;
;                         cur = nxt;
;                     }
	v_pk_mul_f32 v[84:85], v[32:33], v[40:41] op_sel_hi:[1,0]
	ds_read_b128 v[68:71], v97 offset:5632
	v_pk_fma_f32 v[84:85], v[34:35], v[40:41], v[84:85] op_sel:[0,1,0] op_sel_hi:[1,1,1]
	ds_read_b64 v[58:59], v98 offset:4608
	v_pk_fma_f32 v[84:85], v[36:37], v[42:43], v[84:85] op_sel_hi:[1,0,1]
	ds_read_b128 v[72:75], v97 offset:5120
	v_pk_fma_f32 v[84:85], v[38:39], v[42:43], v[84:85] op_sel:[0,1,0] op_sel_hi:[1,1,1]
	ds_read_b128 v[76:79], v97 offset:4864
	v_pk_mul_f32 v[94:95], v[32:33], v[80:81] op_sel_hi:[1,0]
	v_cndmask_b32_e32 v122, v56, v57, vcc
	v_cndmask_b32_e32 v123, v57, v56, vcc
	v_add_f32_dpp v84, v85, v84 quad_perm:[1,0,3,2] row_mask:0xf bank_mask:0xf bound_ctrl:1
	v_pk_fma_f32 v[94:95], v[34:35], v[80:81], v[94:95] op_sel:[0,1,0] op_sel_hi:[1,1,1]
	v_pk_mul_f32 v[86:87], v[122:123], v[48:49] op_sel_hi:[1,0]
	v_add_f32_dpp v84, v84, v84 quad_perm:[2,3,0,1] row_mask:0xf bank_mask:0xf bound_ctrl:1
	v_pk_fma_f32 v[94:95], v[36:37], v[82:83], v[94:95] op_sel_hi:[1,0,1]
	v_pk_mul_f32 v[88:89], v[122:123], v[48:49] op_sel:[0,1] op_sel_hi:[1,1]
	v_add_f32_dpp v84, v84, v84 row_ror:4 row_mask:0xf bank_mask:0xf bound_ctrl:1
	v_pk_fma_f32 v[94:95], v[38:39], v[82:83], v[94:95] op_sel:[0,1,0] op_sel_hi:[1,1,1]
	v_pk_mul_f32 v[90:91], v[122:123], v[50:51] op_sel_hi:[1,0]
	v_add_f32_dpp v84, v84, v84 row_ror:8 row_mask:0xf bank_mask:0xf bound_ctrl:1
	v_pk_mul_f32 v[92:93], v[122:123], v[50:51] op_sel:[0,1] op_sel_hi:[1,1]
	v_add_f32_dpp v96, v95, v94 quad_perm:[1,0,3,2] row_mask:0xf bank_mask:0xf bound_ctrl:1
	ds_read_b128 v[80:83], v97 offset:4608
	v_mov_b32_dpp v85, v84 quad_perm:[1,0,3,2] row_mask:0xf bank_mask:0xf
	ds_write_b32 v99, v96 offset:1024
	v_pk_fma_f32 v[86:87], v[84:85], v[44:45], v[86:87] op_sel_hi:[1,0,1]
	v_pk_fma_f32 v[88:89], v[84:85], v[44:45], v[88:89] op_sel:[0,1,0] op_sel_hi:[1,1,1]
	v_pk_fma_f32 v[90:91], v[84:85], v[46:47], v[90:91] op_sel_hi:[1,0,1]
	v_pk_fma_f32 v[92:93], v[84:85], v[46:47], v[92:93] op_sel:[0,1,0] op_sel_hi:[1,1,1]
	v_pk_fma_f32 v[32:33], v[32:33], v[52:53], v[86:87] op_sel_hi:[1,0,1]
	v_pk_fma_f32 v[34:35], v[34:35], v[52:53], v[88:89] op_sel:[0,1,0] op_sel_hi:[1,1,1]
	v_pk_fma_f32 v[36:37], v[36:37], v[54:55], v[90:91] op_sel_hi:[1,0,1]
	v_pk_fma_f32 v[38:39], v[38:39], v[54:55], v[92:93] op_sel:[0,1,0] op_sel_hi:[1,1,1]
	ds_read_b128 v[40:43], v97 offset:6912
	s_waitcnt lgkmcnt(3)
	v_pk_mul_f32 v[84:85], v[32:33], v[64:65] op_sel_hi:[1,0]
	ds_read_b128 v[44:47], v97 offset:7168
	v_pk_fma_f32 v[84:85], v[34:35], v[64:65], v[84:85] op_sel:[0,1,0] op_sel_hi:[1,1,1]
	ds_read_b64 v[56:57], v98 offset:6144
	v_pk_fma_f32 v[84:85], v[36:37], v[66:67], v[84:85] op_sel_hi:[1,0,1]
	ds_read_b128 v[48:51], v97 offset:6656
	v_pk_fma_f32 v[84:85], v[38:39], v[66:67], v[84:85] op_sel:[0,1,0] op_sel_hi:[1,1,1]
	ds_read_b128 v[52:55], v97 offset:6400
	v_pk_mul_f32 v[94:95], v[32:33], v[60:61] op_sel_hi:[1,0]
	v_cndmask_b32_e32 v122, v58, v59, vcc
	v_cndmask_b32_e32 v123, v59, v58, vcc
	v_add_f32_dpp v84, v85, v84 quad_perm:[1,0,3,2] row_mask:0xf bank_mask:0xf bound_ctrl:1
	v_pk_fma_f32 v[94:95], v[34:35], v[60:61], v[94:95] op_sel:[0,1,0] op_sel_hi:[1,1,1]
	v_pk_mul_f32 v[86:87], v[122:123], v[72:73] op_sel_hi:[1,0]
	v_add_f32_dpp v84, v84, v84 quad_perm:[2,3,0,1] row_mask:0xf bank_mask:0xf bound_ctrl:1
	v_pk_fma_f32 v[94:95], v[36:37], v[62:63], v[94:95] op_sel_hi:[1,0,1]
	v_pk_mul_f32 v[88:89], v[122:123], v[72:73] op_sel:[0,1] op_sel_hi:[1,1]
	v_add_f32_dpp v84, v84, v84 row_ror:4 row_mask:0xf bank_mask:0xf bound_ctrl:1
	v_pk_fma_f32 v[94:95], v[38:39], v[62:63], v[94:95] op_sel:[0,1,0] op_sel_hi:[1,1,1]
	v_pk_mul_f32 v[90:91], v[122:123], v[74:75] op_sel_hi:[1,0]
	v_add_f32_dpp v84, v84, v84 row_ror:8 row_mask:0xf bank_mask:0xf bound_ctrl:1
	v_pk_mul_f32 v[92:93], v[122:123], v[74:75] op_sel:[0,1] op_sel_hi:[1,1]
	v_add_f32_dpp v96, v95, v94 quad_perm:[1,0,3,2] row_mask:0xf bank_mask:0xf bound_ctrl:1
	ds_read_b128 v[60:63], v97 offset:6144
	v_mov_b32_dpp v85, v84 quad_perm:[1,0,3,2] row_mask:0xf bank_mask:0xf
	ds_write_b32 v99, v96 offset:2048
	v_pk_fma_f32 v[86:87], v[84:85], v[68:69], v[86:87] op_sel_hi:[1,0,1]
	v_pk_fma_f32 v[88:89], v[84:85], v[68:69], v[88:89] op_sel:[0,1,0] op_sel_hi:[1,1,1]
	v_pk_fma_f32 v[90:91], v[84:85], v[70:71], v[90:91] op_sel_hi:[1,0,1]
	v_pk_fma_f32 v[92:93], v[84:85], v[70:71], v[92:93] op_sel:[0,1,0] op_sel_hi:[1,1,1]
	v_pk_fma_f32 v[32:33], v[32:33], v[76:77], v[86:87] op_sel_hi:[1,0,1]
	v_pk_fma_f32 v[34:35], v[34:35], v[76:77], v[88:89] op_sel:[0,1,0] op_sel_hi:[1,1,1]
	v_pk_fma_f32 v[36:37], v[36:37], v[78:79], v[90:91] op_sel_hi:[1,0,1]
	v_pk_fma_f32 v[38:39], v[38:39], v[78:79], v[92:93] op_sel:[0,1,0] op_sel_hi:[1,1,1]
	ds_read_b128 v[64:67], v97 offset:8448
	s_waitcnt lgkmcnt(3)
; #define LAS __attribute__((address_space(3)))
; __device__ __forceinline__ float reduce8(float x) { x += dppf<0xB1>(x); x += dppf<0x4E>(x); x += dppf<0x141>(x); return x; }
; __device__ __forceinline__ void phase_scan(CParams& p, LAS unsigned char* lds) {
;     ...
;             for (int c = 0; c < nch; ++c) {
;                 const LAS float* base = (const LAS float*)(lds + (c & 1) * SBUF) + 4 * j;
;                 const LAS float* vb = (const LAS float*)(lds + (c & 1) * SBUF) + 320 + row;
;                 const int nst = (T - c * SCH) < SCH ? (T - c * SCH) : SCH;
;                 ScanOps cur, nxt;
;                 scan_ld(cur, base, vb);
;                 for (int g16 = 0; g16 < nst; g16 += 16) {
;                     unsigned ywb = (unsigned)(YP_OFF + (g16 >> 4) * YP_BYTES + (wid * 64 + lane) * 4);
;                     asm volatile("" : "+v"(ywb));
;                     LAS float* yw = (LAS float*)(lds + ywb);
; #pragma unroll
;                     for (int s16 = 0; s16 < 16; ++s16) {
;                         scan_ld(nxt, base + (g16 + s16 + 1) * 384, vb + (g16 + s16 + 1) * 384);
;                         f32x2 d = S[0] * cur.n0.lo; d = S[1] * cur.n0.hi + d; d = S[2] * cur.n1.lo + d; d = S[3] * cur.n1.hi + d;
;                         const float sa = reduce8(d.x + d.y);
;                         const f32x2 sa2 = (f32x2){sa, sa}, v2 = (f32x2){cur.v, cur.v};
;                         S[0] = S[0] * cur.w0.lo + (cur.b0.lo * sa2 + cur.k0.lo * v2);
;                         S[1] = S[1] * cur.w0.hi + (cur.b0.hi * sa2 + cur.k0.hi * v2);
;                         S[2] = S[2] * cur.w1.lo + (cur.b1.lo * sa2 + cur.k1.lo * v2);
;                         S[3] = S[3] * cur.w1.hi + (cur.b1.hi * sa2 + cur.k1.hi * v2);
;                         f32x2 e = S[0] * cur.r0.lo; e = S[1] * cur.r0.hi + e; e = S[2] * cur.r1.lo + e; e = S[3] * cur.r1.hi + e;
;                         yw[s16 * 256] = e.x + e.y;
;                         cur = nxt;
;                     }
	v_pk_mul_f32 v[84:85], v[32:33], v[40:41] op_sel_hi:[1,0]
	ds_read_b128 v[68:71], v97 offset:8704
	v_pk_fma_f32 v[84:85], v[34:35], v[40:41], v[84:85] op_sel:[0,1,0] op_sel_hi:[1,1,1]
	ds_read_b64 v[58:59], v98 offset:7680
	v_pk_fma_f32 v[84:85], v[36:37], v[42:43], v[84:85] op_sel_hi:[1,0,1]
	ds_read_b128 v[72:75], v97 offset:8192
	v_pk_fma_f32 v[84:85], v[38:39], v[42:43], v[84:85] op_sel:[0,1,0] op_sel_hi:[1,1,1]
	ds_read_b128 v[76:79], v97 offset:7936
	v_pk_mul_f32 v[94:95], v[32:33], v[80:81] op_sel_hi:[1,0]
	v_cndmask_b32_e32 v122, v56, v57, vcc
	v_cndmask_b32_e32 v123, v57, v56, vcc
	v_add_f32_dpp v84, v85, v84 quad_perm:[1,0,3,2] row_mask:0xf bank_mask:0xf bound_ctrl:1
	v_pk_fma_f32 v[94:95], v[34:35], v[80:81], v[94:95] op_sel:[0,1,0] op_sel_hi:[1,1,1]
	v_pk_mul_f32 v[86:87], v[122:123], v[48:49] op_sel_hi:[1,0]
	v_add_f32_dpp v84, v84, v84 quad_perm:[2,3,0,1] row_mask:0xf bank_mask:0xf bound_ctrl:1
	v_pk_fma_f32 v[94:95], v[36:37], v[82:83], v[94:95] op_sel_hi:[1,0,1]
	v_pk_mul_f32 v[88:89], v[122:123], v[48:49] op_sel:[0,1] op_sel_hi:[1,1]
	v_add_f32_dpp v84, v84, v84 row_ror:4 row_mask:0xf bank_mask:0xf bound_ctrl:1
	v_pk_fma_f32 v[94:95], v[38:39], v[82:83], v[94:95] op_sel:[0,1,0] op_sel_hi:[1,1,1]
	v_pk_mul_f32 v[90:91], v[122:123], v[50:51] op_sel_hi:[1,0]
	v_add_f32_dpp v84, v84, v84 row_ror:8 row_mask:0xf bank_mask:0xf bound_ctrl:1
	v_pk_mul_f32 v[92:93], v[122:123], v[50:51] op_sel:[0,1] op_sel_hi:[1,1]
	v_add_f32_dpp v96, v95, v94 quad_perm:[1,0,3,2] row_mask:0xf bank_mask:0xf bound_ctrl:1
	ds_read_b128 v[80:83], v97 offset:7680
	v_mov_b32_dpp v85, v84 quad_perm:[1,0,3,2] row_mask:0xf bank_mask:0xf
	ds_write_b32 v99, v96 offset:3072
	v_pk_fma_f32 v[86:87], v[84:85], v[44:45], v[86:87] op_sel_hi:[1,0,1]
	v_pk_fma_f32 v[88:89], v[84:85], v[44:45], v[88:89] op_sel:[0,1,0] op_sel_hi:[1,1,1]
	v_pk_fma_f32 v[90:91], v[84:85], v[46:47], v[90:91] op_sel_hi:[1,0,1]
	v_pk_fma_f32 v[92:93], v[84:85], v[46:47], v[92:93] op_sel:[0,1,0] op_sel_hi:[1,1,1]
	v_pk_fma_f32 v[32:33], v[32:33], v[52:53], v[86:87] op_sel_hi:[1,0,1]
	v_pk_fma_f32 v[34:35], v[34:35], v[52:53], v[88:89] op_sel:[0,1,0] op_sel_hi:[1,1,1]
	v_pk_fma_f32 v[36:37], v[36:37], v[54:55], v[90:91] op_sel_hi:[1,0,1]
	v_pk_fma_f32 v[38:39], v[38:39], v[54:55], v[92:93] op_sel:[0,1,0] op_sel_hi:[1,1,1]
	ds_read_b128 v[40:43], v97 offset:9984
	s_waitcnt lgkmcnt(3)
	v_pk_mul_f32 v[84:85], v[32:33], v[64:65] op_sel_hi:[1,0]
	ds_read_b128 v[44:47], v97 offset:10240
	v_pk_fma_f32 v[84:85], v[34:35], v[64:65], v[84:85] op_sel:[0,1,0] op_sel_hi:[1,1,1]
	ds_read_b64 v[56:57], v98 offset:9216
	v_pk_fma_f32 v[84:85], v[36:37], v[66:67], v[84:85] op_sel_hi:[1,0,1]
	ds_read_b128 v[48:51], v97 offset:9728
	v_pk_fma_f32 v[84:85], v[38:39], v[66:67], v[84:85] op_sel:[0,1,0] op_sel_hi:[1,1,1]
	ds_read_b128 v[52:55], v97 offset:9472
	v_pk_mul_f32 v[94:95], v[32:33], v[60:61] op_sel_hi:[1,0]
	v_cndmask_b32_e32 v122, v58, v59, vcc
	v_cndmask_b32_e32 v123, v59, v58, vcc
	v_add_f32_dpp v84, v85, v84 quad_perm:[1,0,3,2] row_mask:0xf bank_mask:0xf bound_ctrl:1
	v_pk_fma_f32 v[94:95], v[34:35], v[60:61], v[94:95] op_sel:[0,1,0] op_sel_hi:[1,1,1]
	v_pk_mul_f32 v[86:87], v[122:123], v[72:73] op_sel_hi:[1,0]
	v_add_f32_dpp v84, v84, v84 quad_perm:[2,3,0,1] row_mask:0xf bank_mask:0xf bound_ctrl:1
	v_pk_fma_f32 v[94:95], v[36:37], v[62:63], v[94:95] op_sel_hi:[1,0,1]
	v_pk_mul_f32 v[88:89], v[122:123], v[72:73] op_sel:[0,1] op_sel_hi:[1,1]
	v_add_f32_dpp v84, v84, v84 row_ror:4 row_mask:0xf bank_mask:0xf bound_ctrl:1
	v_pk_fma_f32 v[94:95], v[38:39], v[62:63], v[94:95] op_sel:[0,1,0] op_sel_hi:[1,1,1]
	v_pk_mul_f32 v[90:91], v[122:123], v[74:75] op_sel_hi:[1,0]
	v_add_f32_dpp v84, v84, v84 row_ror:8 row_mask:0xf bank_mask:0xf bound_ctrl:1
	v_pk_mul_f32 v[92:93], v[122:123], v[74:75] op_sel:[0,1] op_sel_hi:[1,1]
	v_add_f32_dpp v96, v95, v94 quad_perm:[1,0,3,2] row_mask:0xf bank_mask:0xf bound_ctrl:1
	ds_read_b128 v[60:63], v97 offset:9216
	v_mov_b32_dpp v85, v84 quad_perm:[1,0,3,2] row_mask:0xf bank_mask:0xf
	ds_write_b32 v99, v96 offset:4096
	v_pk_fma_f32 v[86:87], v[84:85], v[68:69], v[86:87] op_sel_hi:[1,0,1]
	v_pk_fma_f32 v[88:89], v[84:85], v[68:69], v[88:89] op_sel:[0,1,0] op_sel_hi:[1,1,1]
	v_pk_fma_f32 v[90:91], v[84:85], v[70:71], v[90:91] op_sel_hi:[1,0,1]
	v_pk_fma_f32 v[92:93], v[84:85], v[70:71], v[92:93] op_sel:[0,1,0] op_sel_hi:[1,1,1]
	v_pk_fma_f32 v[32:33], v[32:33], v[76:77], v[86:87] op_sel_hi:[1,0,1]
	v_pk_fma_f32 v[34:35], v[34:35], v[76:77], v[88:89] op_sel:[0,1,0] op_sel_hi:[1,1,1]
	v_pk_fma_f32 v[36:37], v[36:37], v[78:79], v[90:91] op_sel_hi:[1,0,1]
	v_pk_fma_f32 v[38:39], v[38:39], v[78:79], v[92:93] op_sel:[0,1,0] op_sel_hi:[1,1,1]
	ds_read_b128 v[64:67], v97 offset:11520
	s_waitcnt lgkmcnt(3)
; __device__ __forceinline__ float reduce8(float x) { x += dppf<0xB1>(x); x += dppf<0x4E>(x); x += dppf<0x141>(x); return x; }
; __device__ __forceinline__ void phase_scan(CParams& p, LAS unsigned char* lds) {
;     ...
;                     for (int s16 = 0; s16 < 16; ++s16) {
;                         scan_ld(nxt, base + (g16 + s16 + 1) * 384, vb + (g16 + s16 + 1) * 384);
;                         f32x2 d = S[0] * cur.n0.lo; d = S[1] * cur.n0.hi + d; d = S[2] * cur.n1.lo + d; d = S[3] * cur.n1.hi + d;
;                         const float sa = reduce8(d.x + d.y);
;                         const f32x2 sa2 = (f32x2){sa, sa}, v2 = (f32x2){cur.v, cur.v};
;                         S[0] = S[0] * cur.w0.lo + (cur.b0.lo * sa2 + cur.k0.lo * v2);
;                         S[1] = S[1] * cur.w0.hi + (cur.b0.hi * sa2 + cur.k0.hi * v2);
;                         S[2] = S[2] * cur.w1.lo + (cur.b1.lo * sa2 + cur.k1.lo * v2);
;                         S[3] = S[3] * cur.w1.hi + (cur.b1.hi * sa2 + cur.k1.hi * v2);
;                         f32x2 e = S[0] * cur.r0.lo; e = S[1] * cur.r0.hi + e; e = S[2] * cur.r1.lo + e; e = S[3] * cur.r1.hi + e;
;                         yw[s16 * 256] = e.x + e.y;
;                         cur = nxt;
;                     }
	v_pk_mul_f32 v[84:85], v[32:33], v[40:41] op_sel_hi:[1,0]
	ds_read_b128 v[68:71], v97 offset:11776
	v_pk_fma_f32 v[84:85], v[34:35], v[40:41], v[84:85] op_sel:[0,1,0] op_sel_hi:[1,1,1]
	ds_read_b64 v[58:59], v98 offset:10752
	v_pk_fma_f32 v[84:85], v[36:37], v[42:43], v[84:85] op_sel_hi:[1,0,1]
	ds_read_b128 v[72:75], v97 offset:11264
	v_pk_fma_f32 v[84:85], v[38:39], v[42:43], v[84:85] op_sel:[0,1,0] op_sel_hi:[1,1,1]
	ds_read_b128 v[76:79], v97 offset:11008
	v_pk_mul_f32 v[94:95], v[32:33], v[80:81] op_sel_hi:[1,0]
	v_cndmask_b32_e32 v122, v56, v57, vcc
	v_cndmask_b32_e32 v123, v57, v56, vcc
	v_add_f32_dpp v84, v85, v84 quad_perm:[1,0,3,2] row_mask:0xf bank_mask:0xf bound_ctrl:1
	v_pk_fma_f32 v[94:95], v[34:35], v[80:81], v[94:95] op_sel:[0,1,0] op_sel_hi:[1,1,1]
	v_pk_mul_f32 v[86:87], v[122:123], v[48:49] op_sel_hi:[1,0]
	v_add_f32_dpp v84, v84, v84 quad_perm:[2,3,0,1] row_mask:0xf bank_mask:0xf bound_ctrl:1
	v_pk_fma_f32 v[94:95], v[36:37], v[82:83], v[94:95] op_sel_hi:[1,0,1]
	v_pk_mul_f32 v[88:89], v[122:123], v[48:49] op_sel:[0,1] op_sel_hi:[1,1]
	v_add_f32_dpp v84, v84, v84 row_ror:4 row_mask:0xf bank_mask:0xf bound_ctrl:1
	v_pk_fma_f32 v[94:95], v[38:39], v[82:83], v[94:95] op_sel:[0,1,0] op_sel_hi:[1,1,1]
	v_pk_mul_f32 v[90:91], v[122:123], v[50:51] op_sel_hi:[1,0]
	v_add_f32_dpp v84, v84, v84 row_ror:8 row_mask:0xf bank_mask:0xf bound_ctrl:1
	v_pk_mul_f32 v[92:93], v[122:123], v[50:51] op_sel:[0,1] op_sel_hi:[1,1]
	v_add_f32_dpp v96, v95, v94 quad_perm:[1,0,3,2] row_mask:0xf bank_mask:0xf bound_ctrl:1
	ds_read_b128 v[80:83], v97 offset:10752
	v_mov_b32_dpp v85, v84 quad_perm:[1,0,3,2] row_mask:0xf bank_mask:0xf
	ds_write_b32 v99, v96 offset:5120
	v_pk_fma_f32 v[86:87], v[84:85], v[44:45], v[86:87] op_sel_hi:[1,0,1]
	v_pk_fma_f32 v[88:89], v[84:85], v[44:45], v[88:89] op_sel:[0,1,0] op_sel_hi:[1,1,1]
	v_pk_fma_f32 v[90:91], v[84:85], v[46:47], v[90:91] op_sel_hi:[1,0,1]
	v_pk_fma_f32 v[92:93], v[84:85], v[46:47], v[92:93] op_sel:[0,1,0] op_sel_hi:[1,1,1]
	v_pk_fma_f32 v[32:33], v[32:33], v[52:53], v[86:87] op_sel_hi:[1,0,1]
	v_pk_fma_f32 v[34:35], v[34:35], v[52:53], v[88:89] op_sel:[0,1,0] op_sel_hi:[1,1,1]
	v_pk_fma_f32 v[36:37], v[36:37], v[54:55], v[90:91] op_sel_hi:[1,0,1]
	v_pk_fma_f32 v[38:39], v[38:39], v[54:55], v[92:93] op_sel:[0,1,0] op_sel_hi:[1,1,1]
	ds_read_b128 v[40:43], v97 offset:13056
	s_waitcnt lgkmcnt(3)
	v_pk_mul_f32 v[84:85], v[32:33], v[64:65] op_sel_hi:[1,0]
	ds_read_b128 v[44:47], v97 offset:13312
	v_pk_fma_f32 v[84:85], v[34:35], v[64:65], v[84:85] op_sel:[0,1,0] op_sel_hi:[1,1,1]
	ds_read_b64 v[56:57], v98 offset:12288
	v_pk_fma_f32 v[84:85], v[36:37], v[66:67], v[84:85] op_sel_hi:[1,0,1]
	ds_read_b128 v[48:51], v97 offset:12800
	v_pk_fma_f32 v[84:85], v[38:39], v[66:67], v[84:85] op_sel:[0,1,0] op_sel_hi:[1,1,1]
	ds_read_b128 v[52:55], v97 offset:12544
	v_pk_mul_f32 v[94:95], v[32:33], v[60:61] op_sel_hi:[1,0]
	v_cndmask_b32_e32 v122, v58, v59, vcc
	v_cndmask_b32_e32 v123, v59, v58, vcc
	v_add_f32_dpp v84, v85, v84 quad_perm:[1,0,3,2] row_mask:0xf bank_mask:0xf bound_ctrl:1
	v_pk_fma_f32 v[94:95], v[34:35], v[60:61], v[94:95] op_sel:[0,1,0] op_sel_hi:[1,1,1]
	v_pk_mul_f32 v[86:87], v[122:123], v[72:73] op_sel_hi:[1,0]
	v_add_f32_dpp v84, v84, v84 quad_perm:[2,3,0,1] row_mask:0xf bank_mask:0xf bound_ctrl:1
	v_pk_fma_f32 v[94:95], v[36:37], v[62:63], v[94:95] op_sel_hi:[1,0,1]
	v_pk_mul_f32 v[88:89], v[122:123], v[72:73] op_sel:[0,1] op_sel_hi:[1,1]
	v_add_f32_dpp v84, v84, v84 row_ror:4 row_mask:0xf bank_mask:0xf bound_ctrl:1
	v_pk_fma_f32 v[94:95], v[38:39], v[62:63], v[94:95] op_sel:[0,1,0] op_sel_hi:[1,1,1]
	v_pk_mul_f32 v[90:91], v[122:123], v[74:75] op_sel_hi:[1,0]
	v_add_f32_dpp v84, v84, v84 row_ror:8 row_mask:0xf bank_mask:0xf bound_ctrl:1
	v_pk_mul_f32 v[92:93], v[122:123], v[74:75] op_sel:[0,1] op_sel_hi:[1,1]
	v_add_f32_dpp v96, v95, v94 quad_perm:[1,0,3,2] row_mask:0xf bank_mask:0xf bound_ctrl:1
	ds_read_b128 v[60:63], v97 offset:12288
	v_mov_b32_dpp v85, v84 quad_perm:[1,0,3,2] row_mask:0xf bank_mask:0xf
	ds_write_b32 v99, v96 offset:6144
	v_pk_fma_f32 v[86:87], v[84:85], v[68:69], v[86:87] op_sel_hi:[1,0,1]
	v_pk_fma_f32 v[88:89], v[84:85], v[68:69], v[88:89] op_sel:[0,1,0] op_sel_hi:[1,1,1]
	v_pk_fma_f32 v[90:91], v[84:85], v[70:71], v[90:91] op_sel_hi:[1,0,1]
	v_pk_fma_f32 v[92:93], v[84:85], v[70:71], v[92:93] op_sel:[0,1,0] op_sel_hi:[1,1,1]
	v_pk_fma_f32 v[32:33], v[32:33], v[76:77], v[86:87] op_sel_hi:[1,0,1]
	v_pk_fma_f32 v[34:35], v[34:35], v[76:77], v[88:89] op_sel:[0,1,0] op_sel_hi:[1,1,1]
	v_pk_fma_f32 v[36:37], v[36:37], v[78:79], v[90:91] op_sel_hi:[1,0,1]
	v_pk_fma_f32 v[38:39], v[38:39], v[78:79], v[92:93] op_sel:[0,1,0] op_sel_hi:[1,1,1]
	ds_read_b128 v[64:67], v97 offset:14592
	s_waitcnt lgkmcnt(3)
; __device__ __forceinline__ float reduce8(float x) { x += dppf<0xB1>(x); x += dppf<0x4E>(x); x += dppf<0x141>(x); return x; }
; __device__ __forceinline__ void phase_scan(CParams& p, LAS unsigned char* lds) {
;     ...
;                     for (int s16 = 0; s16 < 16; ++s16) {
;                         scan_ld(nxt, base + (g16 + s16 + 1) * 384, vb + (g16 + s16 + 1) * 384);
;                         f32x2 d = S[0] * cur.n0.lo; d = S[1] * cur.n0.hi + d; d = S[2] * cur.n1.lo + d; d = S[3] * cur.n1.hi + d;
;                         const float sa = reduce8(d.x + d.y);
;                         const f32x2 sa2 = (f32x2){sa, sa}, v2 = (f32x2){cur.v, cur.v};
;                         S[0] = S[0] * cur.w0.lo + (cur.b0.lo * sa2 + cur.k0.lo * v2);
;                         S[1] = S[1] * cur.w0.hi + (cur.b0.hi * sa2 + cur.k0.hi * v2);
;                         S[2] = S[2] * cur.w1.lo + (cur.b1.lo * sa2 + cur.k1.lo * v2);
;                         S[3] = S[3] * cur.w1.hi + (cur.b1.hi * sa2 + cur.k1.hi * v2);
;                         f32x2 e = S[0] * cur.r0.lo; e = S[1] * cur.r0.hi + e; e = S[2] * cur.r1.lo + e; e = S[3] * cur.r1.hi + e;
;                         yw[s16 * 256] = e.x + e.y;
;                         cur = nxt;
;                     }
	v_pk_mul_f32 v[84:85], v[32:33], v[40:41] op_sel_hi:[1,0]
	ds_read_b128 v[68:71], v97 offset:14848
	v_pk_fma_f32 v[84:85], v[34:35], v[40:41], v[84:85] op_sel:[0,1,0] op_sel_hi:[1,1,1]
	ds_read_b64 v[58:59], v98 offset:13824
	v_pk_fma_f32 v[84:85], v[36:37], v[42:43], v[84:85] op_sel_hi:[1,0,1]
	ds_read_b128 v[72:75], v97 offset:14336
	v_pk_fma_f32 v[84:85], v[38:39], v[42:43], v[84:85] op_sel:[0,1,0] op_sel_hi:[1,1,1]
	ds_read_b128 v[76:79], v97 offset:14080
	v_pk_mul_f32 v[94:95], v[32:33], v[80:81] op_sel_hi:[1,0]
	v_cndmask_b32_e32 v122, v56, v57, vcc
	v_cndmask_b32_e32 v123, v57, v56, vcc
	v_add_f32_dpp v84, v85, v84 quad_perm:[1,0,3,2] row_mask:0xf bank_mask:0xf bound_ctrl:1
	v_pk_fma_f32 v[94:95], v[34:35], v[80:81], v[94:95] op_sel:[0,1,0] op_sel_hi:[1,1,1]
	v_pk_mul_f32 v[86:87], v[122:123], v[48:49] op_sel_hi:[1,0]
	v_add_f32_dpp v84, v84, v84 quad_perm:[2,3,0,1] row_mask:0xf bank_mask:0xf bound_ctrl:1
	v_pk_fma_f32 v[94:95], v[36:37], v[82:83], v[94:95] op_sel_hi:[1,0,1]
	v_pk_mul_f32 v[88:89], v[122:123], v[48:49] op_sel:[0,1] op_sel_hi:[1,1]
	v_add_f32_dpp v84, v84, v84 row_ror:4 row_mask:0xf bank_mask:0xf bound_ctrl:1
	v_pk_fma_f32 v[94:95], v[38:39], v[82:83], v[94:95] op_sel:[0,1,0] op_sel_hi:[1,1,1]
	v_pk_mul_f32 v[90:91], v[122:123], v[50:51] op_sel_hi:[1,0]
	v_add_f32_dpp v84, v84, v84 row_ror:8 row_mask:0xf bank_mask:0xf bound_ctrl:1
	v_pk_mul_f32 v[92:93], v[122:123], v[50:51] op_sel:[0,1] op_sel_hi:[1,1]
	v_add_f32_dpp v96, v95, v94 quad_perm:[1,0,3,2] row_mask:0xf bank_mask:0xf bound_ctrl:1
	ds_read_b128 v[80:83], v97 offset:13824
	v_mov_b32_dpp v85, v84 quad_perm:[1,0,3,2] row_mask:0xf bank_mask:0xf
	ds_write_b32 v99, v96 offset:7168
	v_pk_fma_f32 v[86:87], v[84:85], v[44:45], v[86:87] op_sel_hi:[1,0,1]
	v_pk_fma_f32 v[88:89], v[84:85], v[44:45], v[88:89] op_sel:[0,1,0] op_sel_hi:[1,1,1]
	v_pk_fma_f32 v[90:91], v[84:85], v[46:47], v[90:91] op_sel_hi:[1,0,1]
	v_pk_fma_f32 v[92:93], v[84:85], v[46:47], v[92:93] op_sel:[0,1,0] op_sel_hi:[1,1,1]
	v_pk_fma_f32 v[32:33], v[32:33], v[52:53], v[86:87] op_sel_hi:[1,0,1]
	v_pk_fma_f32 v[34:35], v[34:35], v[52:53], v[88:89] op_sel:[0,1,0] op_sel_hi:[1,1,1]
	v_pk_fma_f32 v[36:37], v[36:37], v[54:55], v[90:91] op_sel_hi:[1,0,1]
	v_pk_fma_f32 v[38:39], v[38:39], v[54:55], v[92:93] op_sel:[0,1,0] op_sel_hi:[1,1,1]
	ds_read_b128 v[40:43], v97 offset:16128
	s_waitcnt lgkmcnt(3)
	v_pk_mul_f32 v[84:85], v[32:33], v[64:65] op_sel_hi:[1,0]
	ds_read_b128 v[44:47], v97 offset:16384
	v_pk_fma_f32 v[84:85], v[34:35], v[64:65], v[84:85] op_sel:[0,1,0] op_sel_hi:[1,1,1]
	ds_read_b64 v[56:57], v98 offset:15360
	v_pk_fma_f32 v[84:85], v[36:37], v[66:67], v[84:85] op_sel_hi:[1,0,1]
	ds_read_b128 v[48:51], v97 offset:15872
	v_pk_fma_f32 v[84:85], v[38:39], v[66:67], v[84:85] op_sel:[0,1,0] op_sel_hi:[1,1,1]
	ds_read_b128 v[52:55], v97 offset:15616
	v_pk_mul_f32 v[94:95], v[32:33], v[60:61] op_sel_hi:[1,0]
	v_cndmask_b32_e32 v122, v58, v59, vcc
	v_cndmask_b32_e32 v123, v59, v58, vcc
	v_add_f32_dpp v84, v85, v84 quad_perm:[1,0,3,2] row_mask:0xf bank_mask:0xf bound_ctrl:1
	v_pk_fma_f32 v[94:95], v[34:35], v[60:61], v[94:95] op_sel:[0,1,0] op_sel_hi:[1,1,1]
	v_pk_mul_f32 v[86:87], v[122:123], v[72:73] op_sel_hi:[1,0]
	v_add_f32_dpp v84, v84, v84 quad_perm:[2,3,0,1] row_mask:0xf bank_mask:0xf bound_ctrl:1
	v_pk_fma_f32 v[94:95], v[36:37], v[62:63], v[94:95] op_sel_hi:[1,0,1]
	v_pk_mul_f32 v[88:89], v[122:123], v[72:73] op_sel:[0,1] op_sel_hi:[1,1]
	v_add_f32_dpp v84, v84, v84 row_ror:4 row_mask:0xf bank_mask:0xf bound_ctrl:1
	v_pk_fma_f32 v[94:95], v[38:39], v[62:63], v[94:95] op_sel:[0,1,0] op_sel_hi:[1,1,1]
	v_pk_mul_f32 v[90:91], v[122:123], v[74:75] op_sel_hi:[1,0]
	v_add_f32_dpp v84, v84, v84 row_ror:8 row_mask:0xf bank_mask:0xf bound_ctrl:1
	v_pk_mul_f32 v[92:93], v[122:123], v[74:75] op_sel:[0,1] op_sel_hi:[1,1]
	v_add_f32_dpp v96, v95, v94 quad_perm:[1,0,3,2] row_mask:0xf bank_mask:0xf bound_ctrl:1
	ds_read_b128 v[60:63], v97 offset:15360
	v_mov_b32_dpp v85, v84 quad_perm:[1,0,3,2] row_mask:0xf bank_mask:0xf
	ds_write_b32 v99, v96 offset:8192
	v_pk_fma_f32 v[86:87], v[84:85], v[68:69], v[86:87] op_sel_hi:[1,0,1]
	v_pk_fma_f32 v[88:89], v[84:85], v[68:69], v[88:89] op_sel:[0,1,0] op_sel_hi:[1,1,1]
	v_pk_fma_f32 v[90:91], v[84:85], v[70:71], v[90:91] op_sel_hi:[1,0,1]
	v_pk_fma_f32 v[92:93], v[84:85], v[70:71], v[92:93] op_sel:[0,1,0] op_sel_hi:[1,1,1]
	v_pk_fma_f32 v[32:33], v[32:33], v[76:77], v[86:87] op_sel_hi:[1,0,1]
	v_pk_fma_f32 v[34:35], v[34:35], v[76:77], v[88:89] op_sel:[0,1,0] op_sel_hi:[1,1,1]
	v_pk_fma_f32 v[36:37], v[36:37], v[78:79], v[90:91] op_sel_hi:[1,0,1]
	v_pk_fma_f32 v[38:39], v[38:39], v[78:79], v[92:93] op_sel:[0,1,0] op_sel_hi:[1,1,1]
	ds_read_b128 v[64:67], v97 offset:17664
	s_waitcnt lgkmcnt(3)
; __device__ __forceinline__ float reduce8(float x) { x += dppf<0xB1>(x); x += dppf<0x4E>(x); x += dppf<0x141>(x); return x; }
; __device__ __forceinline__ void phase_scan(CParams& p, LAS unsigned char* lds) {
;     ...
;                     for (int s16 = 0; s16 < 16; ++s16) {
;                         scan_ld(nxt, base + (g16 + s16 + 1) * 384, vb + (g16 + s16 + 1) * 384);
;                         f32x2 d = S[0] * cur.n0.lo; d = S[1] * cur.n0.hi + d; d = S[2] * cur.n1.lo + d; d = S[3] * cur.n1.hi + d;
;                         const float sa = reduce8(d.x + d.y);
;                         const f32x2 sa2 = (f32x2){sa, sa}, v2 = (f32x2){cur.v, cur.v};
;                         S[0] = S[0] * cur.w0.lo + (cur.b0.lo * sa2 + cur.k0.lo * v2);
;                         S[1] = S[1] * cur.w0.hi + (cur.b0.hi * sa2 + cur.k0.hi * v2);
;                         S[2] = S[2] * cur.w1.lo + (cur.b1.lo * sa2 + cur.k1.lo * v2);
;                         S[3] = S[3] * cur.w1.hi + (cur.b1.hi * sa2 + cur.k1.hi * v2);
;                         f32x2 e = S[0] * cur.r0.lo; e = S[1] * cur.r0.hi + e; e = S[2] * cur.r1.lo + e; e = S[3] * cur.r1.hi + e;
;                         yw[s16 * 256] = e.x + e.y;
;                         cur = nxt;
;                     }
	v_pk_mul_f32 v[84:85], v[32:33], v[40:41] op_sel_hi:[1,0]
	ds_read_b128 v[68:71], v97 offset:17920
	v_pk_fma_f32 v[84:85], v[34:35], v[40:41], v[84:85] op_sel:[0,1,0] op_sel_hi:[1,1,1]
	ds_read_b64 v[58:59], v98 offset:16896
	v_pk_fma_f32 v[84:85], v[36:37], v[42:43], v[84:85] op_sel_hi:[1,0,1]
	ds_read_b128 v[72:75], v97 offset:17408
	v_pk_fma_f32 v[84:85], v[38:39], v[42:43], v[84:85] op_sel:[0,1,0] op_sel_hi:[1,1,1]
	ds_read_b128 v[76:79], v97 offset:17152
	v_pk_mul_f32 v[94:95], v[32:33], v[80:81] op_sel_hi:[1,0]
	v_cndmask_b32_e32 v122, v56, v57, vcc
	v_cndmask_b32_e32 v123, v57, v56, vcc
	v_add_f32_dpp v84, v85, v84 quad_perm:[1,0,3,2] row_mask:0xf bank_mask:0xf bound_ctrl:1
	v_pk_fma_f32 v[94:95], v[34:35], v[80:81], v[94:95] op_sel:[0,1,0] op_sel_hi:[1,1,1]
	v_pk_mul_f32 v[86:87], v[122:123], v[48:49] op_sel_hi:[1,0]
	v_add_f32_dpp v84, v84, v84 quad_perm:[2,3,0,1] row_mask:0xf bank_mask:0xf bound_ctrl:1
	v_pk_fma_f32 v[94:95], v[36:37], v[82:83], v[94:95] op_sel_hi:[1,0,1]
	v_pk_mul_f32 v[88:89], v[122:123], v[48:49] op_sel:[0,1] op_sel_hi:[1,1]
	v_add_f32_dpp v84, v84, v84 row_ror:4 row_mask:0xf bank_mask:0xf bound_ctrl:1
	v_pk_fma_f32 v[94:95], v[38:39], v[82:83], v[94:95] op_sel:[0,1,0] op_sel_hi:[1,1,1]
	v_pk_mul_f32 v[90:91], v[122:123], v[50:51] op_sel_hi:[1,0]
	v_add_f32_dpp v84, v84, v84 row_ror:8 row_mask:0xf bank_mask:0xf bound_ctrl:1
	v_pk_mul_f32 v[92:93], v[122:123], v[50:51] op_sel:[0,1] op_sel_hi:[1,1]
	v_add_f32_dpp v96, v95, v94 quad_perm:[1,0,3,2] row_mask:0xf bank_mask:0xf bound_ctrl:1
	ds_read_b128 v[80:83], v97 offset:16896
	v_mov_b32_dpp v85, v84 quad_perm:[1,0,3,2] row_mask:0xf bank_mask:0xf
	ds_write_b32 v99, v96 offset:9216
	v_pk_fma_f32 v[86:87], v[84:85], v[44:45], v[86:87] op_sel_hi:[1,0,1]
	v_pk_fma_f32 v[88:89], v[84:85], v[44:45], v[88:89] op_sel:[0,1,0] op_sel_hi:[1,1,1]
	v_pk_fma_f32 v[90:91], v[84:85], v[46:47], v[90:91] op_sel_hi:[1,0,1]
	v_pk_fma_f32 v[92:93], v[84:85], v[46:47], v[92:93] op_sel:[0,1,0] op_sel_hi:[1,1,1]
	v_pk_fma_f32 v[32:33], v[32:33], v[52:53], v[86:87] op_sel_hi:[1,0,1]
	v_pk_fma_f32 v[34:35], v[34:35], v[52:53], v[88:89] op_sel:[0,1,0] op_sel_hi:[1,1,1]
	v_pk_fma_f32 v[36:37], v[36:37], v[54:55], v[90:91] op_sel_hi:[1,0,1]
	v_pk_fma_f32 v[38:39], v[38:39], v[54:55], v[92:93] op_sel:[0,1,0] op_sel_hi:[1,1,1]
	ds_read_b128 v[40:43], v97 offset:19200
	s_waitcnt lgkmcnt(3)
	v_pk_mul_f32 v[84:85], v[32:33], v[64:65] op_sel_hi:[1,0]
	ds_read_b128 v[44:47], v97 offset:19456
	v_pk_fma_f32 v[84:85], v[34:35], v[64:65], v[84:85] op_sel:[0,1,0] op_sel_hi:[1,1,1]
	ds_read_b64 v[56:57], v98 offset:18432
	v_pk_fma_f32 v[84:85], v[36:37], v[66:67], v[84:85] op_sel_hi:[1,0,1]
	ds_read_b128 v[48:51], v97 offset:18944
	v_pk_fma_f32 v[84:85], v[38:39], v[66:67], v[84:85] op_sel:[0,1,0] op_sel_hi:[1,1,1]
	ds_read_b128 v[52:55], v97 offset:18688
	v_pk_mul_f32 v[94:95], v[32:33], v[60:61] op_sel_hi:[1,0]
	v_cndmask_b32_e32 v122, v58, v59, vcc
	v_cndmask_b32_e32 v123, v59, v58, vcc
	v_add_f32_dpp v84, v85, v84 quad_perm:[1,0,3,2] row_mask:0xf bank_mask:0xf bound_ctrl:1
	v_pk_fma_f32 v[94:95], v[34:35], v[60:61], v[94:95] op_sel:[0,1,0] op_sel_hi:[1,1,1]
	v_pk_mul_f32 v[86:87], v[122:123], v[72:73] op_sel_hi:[1,0]
	v_add_f32_dpp v84, v84, v84 quad_perm:[2,3,0,1] row_mask:0xf bank_mask:0xf bound_ctrl:1
	v_pk_fma_f32 v[94:95], v[36:37], v[62:63], v[94:95] op_sel_hi:[1,0,1]
	v_pk_mul_f32 v[88:89], v[122:123], v[72:73] op_sel:[0,1] op_sel_hi:[1,1]
	v_add_f32_dpp v84, v84, v84 row_ror:4 row_mask:0xf bank_mask:0xf bound_ctrl:1
	v_pk_fma_f32 v[94:95], v[38:39], v[62:63], v[94:95] op_sel:[0,1,0] op_sel_hi:[1,1,1]
	v_pk_mul_f32 v[90:91], v[122:123], v[74:75] op_sel_hi:[1,0]
	v_add_f32_dpp v84, v84, v84 row_ror:8 row_mask:0xf bank_mask:0xf bound_ctrl:1
	v_pk_mul_f32 v[92:93], v[122:123], v[74:75] op_sel:[0,1] op_sel_hi:[1,1]
	v_add_f32_dpp v96, v95, v94 quad_perm:[1,0,3,2] row_mask:0xf bank_mask:0xf bound_ctrl:1
	ds_read_b128 v[60:63], v97 offset:18432
	v_mov_b32_dpp v85, v84 quad_perm:[1,0,3,2] row_mask:0xf bank_mask:0xf
	ds_write_b32 v99, v96 offset:10240
	v_pk_fma_f32 v[86:87], v[84:85], v[68:69], v[86:87] op_sel_hi:[1,0,1]
	v_pk_fma_f32 v[88:89], v[84:85], v[68:69], v[88:89] op_sel:[0,1,0] op_sel_hi:[1,1,1]
	v_pk_fma_f32 v[90:91], v[84:85], v[70:71], v[90:91] op_sel_hi:[1,0,1]
	v_pk_fma_f32 v[92:93], v[84:85], v[70:71], v[92:93] op_sel:[0,1,0] op_sel_hi:[1,1,1]
	v_pk_fma_f32 v[32:33], v[32:33], v[76:77], v[86:87] op_sel_hi:[1,0,1]
	v_pk_fma_f32 v[34:35], v[34:35], v[76:77], v[88:89] op_sel:[0,1,0] op_sel_hi:[1,1,1]
	v_pk_fma_f32 v[36:37], v[36:37], v[78:79], v[90:91] op_sel_hi:[1,0,1]
	v_pk_fma_f32 v[38:39], v[38:39], v[78:79], v[92:93] op_sel:[0,1,0] op_sel_hi:[1,1,1]
	ds_read_b128 v[64:67], v97 offset:20736
	s_waitcnt lgkmcnt(3)
; __device__ __forceinline__ float reduce8(float x) { x += dppf<0xB1>(x); x += dppf<0x4E>(x); x += dppf<0x141>(x); return x; }
; __device__ __forceinline__ void phase_scan(CParams& p, LAS unsigned char* lds) {
;     ...
;                     for (int s16 = 0; s16 < 16; ++s16) {
;                         scan_ld(nxt, base + (g16 + s16 + 1) * 384, vb + (g16 + s16 + 1) * 384);
;                         f32x2 d = S[0] * cur.n0.lo; d = S[1] * cur.n0.hi + d; d = S[2] * cur.n1.lo + d; d = S[3] * cur.n1.hi + d;
;                         const float sa = reduce8(d.x + d.y);
;                         const f32x2 sa2 = (f32x2){sa, sa}, v2 = (f32x2){cur.v, cur.v};
;                         S[0] = S[0] * cur.w0.lo + (cur.b0.lo * sa2 + cur.k0.lo * v2);
;                         S[1] = S[1] * cur.w0.hi + (cur.b0.hi * sa2 + cur.k0.hi * v2);
;                         S[2] = S[2] * cur.w1.lo + (cur.b1.lo * sa2 + cur.k1.lo * v2);
;                         S[3] = S[3] * cur.w1.hi + (cur.b1.hi * sa2 + cur.k1.hi * v2);
;                         f32x2 e = S[0] * cur.r0.lo; e = S[1] * cur.r0.hi + e; e = S[2] * cur.r1.lo + e; e = S[3] * cur.r1.hi + e;
;                         yw[s16 * 256] = e.x + e.y;
;                         cur = nxt;
;                     }
	v_pk_mul_f32 v[84:85], v[32:33], v[40:41] op_sel_hi:[1,0]
	ds_read_b128 v[68:71], v97 offset:20992
	v_pk_fma_f32 v[84:85], v[34:35], v[40:41], v[84:85] op_sel:[0,1,0] op_sel_hi:[1,1,1]
	ds_read_b64 v[58:59], v98 offset:19968
	v_pk_fma_f32 v[84:85], v[36:37], v[42:43], v[84:85] op_sel_hi:[1,0,1]
	ds_read_b128 v[72:75], v97 offset:20480
	v_pk_fma_f32 v[84:85], v[38:39], v[42:43], v[84:85] op_sel:[0,1,0] op_sel_hi:[1,1,1]
	ds_read_b128 v[76:79], v97 offset:20224
	v_pk_mul_f32 v[94:95], v[32:33], v[80:81] op_sel_hi:[1,0]
	v_cndmask_b32_e32 v122, v56, v57, vcc
	v_cndmask_b32_e32 v123, v57, v56, vcc
	v_add_f32_dpp v84, v85, v84 quad_perm:[1,0,3,2] row_mask:0xf bank_mask:0xf bound_ctrl:1
	v_pk_fma_f32 v[94:95], v[34:35], v[80:81], v[94:95] op_sel:[0,1,0] op_sel_hi:[1,1,1]
	v_pk_mul_f32 v[86:87], v[122:123], v[48:49] op_sel_hi:[1,0]
	v_add_f32_dpp v84, v84, v84 quad_perm:[2,3,0,1] row_mask:0xf bank_mask:0xf bound_ctrl:1
	v_pk_fma_f32 v[94:95], v[36:37], v[82:83], v[94:95] op_sel_hi:[1,0,1]
	v_pk_mul_f32 v[88:89], v[122:123], v[48:49] op_sel:[0,1] op_sel_hi:[1,1]
	v_add_f32_dpp v84, v84, v84 row_ror:4 row_mask:0xf bank_mask:0xf bound_ctrl:1
	v_pk_fma_f32 v[94:95], v[38:39], v[82:83], v[94:95] op_sel:[0,1,0] op_sel_hi:[1,1,1]
	v_pk_mul_f32 v[90:91], v[122:123], v[50:51] op_sel_hi:[1,0]
	v_add_f32_dpp v84, v84, v84 row_ror:8 row_mask:0xf bank_mask:0xf bound_ctrl:1
	v_pk_mul_f32 v[92:93], v[122:123], v[50:51] op_sel:[0,1] op_sel_hi:[1,1]
	v_add_f32_dpp v96, v95, v94 quad_perm:[1,0,3,2] row_mask:0xf bank_mask:0xf bound_ctrl:1
	ds_read_b128 v[80:83], v97 offset:19968
	v_mov_b32_dpp v85, v84 quad_perm:[1,0,3,2] row_mask:0xf bank_mask:0xf
	ds_write_b32 v99, v96 offset:11264
	v_pk_fma_f32 v[86:87], v[84:85], v[44:45], v[86:87] op_sel_hi:[1,0,1]
	v_pk_fma_f32 v[88:89], v[84:85], v[44:45], v[88:89] op_sel:[0,1,0] op_sel_hi:[1,1,1]
	v_pk_fma_f32 v[90:91], v[84:85], v[46:47], v[90:91] op_sel_hi:[1,0,1]
	v_pk_fma_f32 v[92:93], v[84:85], v[46:47], v[92:93] op_sel:[0,1,0] op_sel_hi:[1,1,1]
	v_pk_fma_f32 v[32:33], v[32:33], v[52:53], v[86:87] op_sel_hi:[1,0,1]
	v_pk_fma_f32 v[34:35], v[34:35], v[52:53], v[88:89] op_sel:[0,1,0] op_sel_hi:[1,1,1]
	v_pk_fma_f32 v[36:37], v[36:37], v[54:55], v[90:91] op_sel_hi:[1,0,1]
	v_pk_fma_f32 v[38:39], v[38:39], v[54:55], v[92:93] op_sel:[0,1,0] op_sel_hi:[1,1,1]
	ds_read_b128 v[40:43], v97 offset:22272
	s_waitcnt lgkmcnt(3)
	v_pk_mul_f32 v[84:85], v[32:33], v[64:65] op_sel_hi:[1,0]
	ds_read_b128 v[44:47], v97 offset:22528
	v_pk_fma_f32 v[84:85], v[34:35], v[64:65], v[84:85] op_sel:[0,1,0] op_sel_hi:[1,1,1]
	ds_read_b64 v[56:57], v98 offset:21504
	v_pk_fma_f32 v[84:85], v[36:37], v[66:67], v[84:85] op_sel_hi:[1,0,1]
	ds_read_b128 v[48:51], v97 offset:22016
	v_pk_fma_f32 v[84:85], v[38:39], v[66:67], v[84:85] op_sel:[0,1,0] op_sel_hi:[1,1,1]
	ds_read_b128 v[52:55], v97 offset:21760
	v_pk_mul_f32 v[94:95], v[32:33], v[60:61] op_sel_hi:[1,0]
	v_cndmask_b32_e32 v122, v58, v59, vcc
	v_cndmask_b32_e32 v123, v59, v58, vcc
	v_add_f32_dpp v84, v85, v84 quad_perm:[1,0,3,2] row_mask:0xf bank_mask:0xf bound_ctrl:1
	v_pk_fma_f32 v[94:95], v[34:35], v[60:61], v[94:95] op_sel:[0,1,0] op_sel_hi:[1,1,1]
	v_pk_mul_f32 v[86:87], v[122:123], v[72:73] op_sel_hi:[1,0]
	v_add_f32_dpp v84, v84, v84 quad_perm:[2,3,0,1] row_mask:0xf bank_mask:0xf bound_ctrl:1
	v_pk_fma_f32 v[94:95], v[36:37], v[62:63], v[94:95] op_sel_hi:[1,0,1]
	v_pk_mul_f32 v[88:89], v[122:123], v[72:73] op_sel:[0,1] op_sel_hi:[1,1]
	v_add_f32_dpp v84, v84, v84 row_ror:4 row_mask:0xf bank_mask:0xf bound_ctrl:1
	v_pk_fma_f32 v[94:95], v[38:39], v[62:63], v[94:95] op_sel:[0,1,0] op_sel_hi:[1,1,1]
	v_pk_mul_f32 v[90:91], v[122:123], v[74:75] op_sel_hi:[1,0]
	v_add_f32_dpp v84, v84, v84 row_ror:8 row_mask:0xf bank_mask:0xf bound_ctrl:1
	v_pk_mul_f32 v[92:93], v[122:123], v[74:75] op_sel:[0,1] op_sel_hi:[1,1]
	v_add_f32_dpp v96, v95, v94 quad_perm:[1,0,3,2] row_mask:0xf bank_mask:0xf bound_ctrl:1
	ds_read_b128 v[60:63], v97 offset:21504
	v_mov_b32_dpp v85, v84 quad_perm:[1,0,3,2] row_mask:0xf bank_mask:0xf
	ds_write_b32 v99, v96 offset:12288
	v_pk_fma_f32 v[86:87], v[84:85], v[68:69], v[86:87] op_sel_hi:[1,0,1]
	v_pk_fma_f32 v[88:89], v[84:85], v[68:69], v[88:89] op_sel:[0,1,0] op_sel_hi:[1,1,1]
	v_pk_fma_f32 v[90:91], v[84:85], v[70:71], v[90:91] op_sel_hi:[1,0,1]
	v_pk_fma_f32 v[92:93], v[84:85], v[70:71], v[92:93] op_sel:[0,1,0] op_sel_hi:[1,1,1]
	v_pk_fma_f32 v[32:33], v[32:33], v[76:77], v[86:87] op_sel_hi:[1,0,1]
	v_pk_fma_f32 v[34:35], v[34:35], v[76:77], v[88:89] op_sel:[0,1,0] op_sel_hi:[1,1,1]
	v_pk_fma_f32 v[36:37], v[36:37], v[78:79], v[90:91] op_sel_hi:[1,0,1]
	v_pk_fma_f32 v[38:39], v[38:39], v[78:79], v[92:93] op_sel:[0,1,0] op_sel_hi:[1,1,1]
	ds_read_b128 v[64:67], v97 offset:23808
	s_waitcnt lgkmcnt(3)
; __device__ __forceinline__ float reduce8(float x) { x += dppf<0xB1>(x); x += dppf<0x4E>(x); x += dppf<0x141>(x); return x; }
; __device__ __forceinline__ void phase_scan(CParams& p, LAS unsigned char* lds) {
;     ...
;                     for (int s16 = 0; s16 < 16; ++s16) {
;                         scan_ld(nxt, base + (g16 + s16 + 1) * 384, vb + (g16 + s16 + 1) * 384);
;                         f32x2 d = S[0] * cur.n0.lo; d = S[1] * cur.n0.hi + d; d = S[2] * cur.n1.lo + d; d = S[3] * cur.n1.hi + d;
;                         const float sa = reduce8(d.x + d.y);
;                         const f32x2 sa2 = (f32x2){sa, sa}, v2 = (f32x2){cur.v, cur.v};
;                         S[0] = S[0] * cur.w0.lo + (cur.b0.lo * sa2 + cur.k0.lo * v2);
;                         S[1] = S[1] * cur.w0.hi + (cur.b0.hi * sa2 + cur.k0.hi * v2);
;                         S[2] = S[2] * cur.w1.lo + (cur.b1.lo * sa2 + cur.k1.lo * v2);
;                         S[3] = S[3] * cur.w1.hi + (cur.b1.hi * sa2 + cur.k1.hi * v2);
;                         f32x2 e = S[0] * cur.r0.lo; e = S[1] * cur.r0.hi + e; e = S[2] * cur.r1.lo + e; e = S[3] * cur.r1.hi + e;
;                         yw[s16 * 256] = e.x + e.y;
;                         cur = nxt;
;                     }
;                     __syncthreads();
;                 }
;             }
;             float* so = p.out + (prompt ? O_WP : O_WS) + ((size_t)chain * 64 + row) * 64;
;             *(f32x4*)(so + 4 * j) = (f32x4){S[0].x, S[0].y, S[1].x, S[1].y}; *(f32x4*)(so + 32 + 4 * j) = (f32x4){S[2].x, S[2].y, S[3].x, S[3].y};
	v_pk_mul_f32 v[84:85], v[32:33], v[40:41] op_sel_hi:[1,0]
	ds_read_b128 v[68:71], v97 offset:24064
	v_pk_fma_f32 v[84:85], v[34:35], v[40:41], v[84:85] op_sel:[0,1,0] op_sel_hi:[1,1,1]
	ds_read_b64 v[58:59], v98 offset:23040
	v_pk_fma_f32 v[84:85], v[36:37], v[42:43], v[84:85] op_sel_hi:[1,0,1]
	ds_read_b128 v[72:75], v97 offset:23552
	v_pk_fma_f32 v[84:85], v[38:39], v[42:43], v[84:85] op_sel:[0,1,0] op_sel_hi:[1,1,1]
	ds_read_b128 v[76:79], v97 offset:23296
	v_pk_mul_f32 v[94:95], v[32:33], v[80:81] op_sel_hi:[1,0]
	v_cndmask_b32_e32 v122, v56, v57, vcc
	v_cndmask_b32_e32 v123, v57, v56, vcc
	v_add_f32_dpp v84, v85, v84 quad_perm:[1,0,3,2] row_mask:0xf bank_mask:0xf bound_ctrl:1
	v_pk_fma_f32 v[94:95], v[34:35], v[80:81], v[94:95] op_sel:[0,1,0] op_sel_hi:[1,1,1]
	v_pk_mul_f32 v[86:87], v[122:123], v[48:49] op_sel_hi:[1,0]
	v_add_f32_dpp v84, v84, v84 quad_perm:[2,3,0,1] row_mask:0xf bank_mask:0xf bound_ctrl:1
	v_pk_fma_f32 v[94:95], v[36:37], v[82:83], v[94:95] op_sel_hi:[1,0,1]
	v_pk_mul_f32 v[88:89], v[122:123], v[48:49] op_sel:[0,1] op_sel_hi:[1,1]
	v_add_f32_dpp v84, v84, v84 row_ror:4 row_mask:0xf bank_mask:0xf bound_ctrl:1
	v_pk_fma_f32 v[94:95], v[38:39], v[82:83], v[94:95] op_sel:[0,1,0] op_sel_hi:[1,1,1]
	v_pk_mul_f32 v[90:91], v[122:123], v[50:51] op_sel_hi:[1,0]
	v_add_f32_dpp v84, v84, v84 row_ror:8 row_mask:0xf bank_mask:0xf bound_ctrl:1
	v_pk_mul_f32 v[92:93], v[122:123], v[50:51] op_sel:[0,1] op_sel_hi:[1,1]
	v_add_f32_dpp v96, v95, v94 quad_perm:[1,0,3,2] row_mask:0xf bank_mask:0xf bound_ctrl:1
	ds_read_b128 v[80:83], v97 offset:23040
	v_mov_b32_dpp v85, v84 quad_perm:[1,0,3,2] row_mask:0xf bank_mask:0xf
	ds_write_b32 v99, v96 offset:13312
	v_pk_fma_f32 v[86:87], v[84:85], v[44:45], v[86:87] op_sel_hi:[1,0,1]
	v_pk_fma_f32 v[88:89], v[84:85], v[44:45], v[88:89] op_sel:[0,1,0] op_sel_hi:[1,1,1]
	v_pk_fma_f32 v[90:91], v[84:85], v[46:47], v[90:91] op_sel_hi:[1,0,1]
	v_pk_fma_f32 v[92:93], v[84:85], v[46:47], v[92:93] op_sel:[0,1,0] op_sel_hi:[1,1,1]
	v_pk_fma_f32 v[32:33], v[32:33], v[52:53], v[86:87] op_sel_hi:[1,0,1]
	v_pk_fma_f32 v[34:35], v[34:35], v[52:53], v[88:89] op_sel:[0,1,0] op_sel_hi:[1,1,1]
	v_pk_fma_f32 v[36:37], v[36:37], v[54:55], v[90:91] op_sel_hi:[1,0,1]
	v_pk_fma_f32 v[38:39], v[38:39], v[54:55], v[92:93] op_sel:[0,1,0] op_sel_hi:[1,1,1]
	ds_read_b128 v[40:43], v97 offset:25344
	s_waitcnt lgkmcnt(3)
	v_pk_mul_f32 v[84:85], v[32:33], v[64:65] op_sel_hi:[1,0]
	ds_read_b128 v[44:47], v97 offset:25600
	v_pk_fma_f32 v[84:85], v[34:35], v[64:65], v[84:85] op_sel:[0,1,0] op_sel_hi:[1,1,1]
	ds_read_b64 v[56:57], v98 offset:24576
	v_pk_fma_f32 v[84:85], v[36:37], v[66:67], v[84:85] op_sel_hi:[1,0,1]
	ds_read_b128 v[48:51], v97 offset:25088
	v_pk_fma_f32 v[84:85], v[38:39], v[66:67], v[84:85] op_sel:[0,1,0] op_sel_hi:[1,1,1]
	ds_read_b128 v[52:55], v97 offset:24832
	v_pk_mul_f32 v[94:95], v[32:33], v[60:61] op_sel_hi:[1,0]
	v_cndmask_b32_e32 v122, v58, v59, vcc
	v_cndmask_b32_e32 v123, v59, v58, vcc
	v_add_f32_dpp v84, v85, v84 quad_perm:[1,0,3,2] row_mask:0xf bank_mask:0xf bound_ctrl:1
	v_pk_fma_f32 v[94:95], v[34:35], v[60:61], v[94:95] op_sel:[0,1,0] op_sel_hi:[1,1,1]
	v_pk_mul_f32 v[86:87], v[122:123], v[72:73] op_sel_hi:[1,0]
	v_add_f32_dpp v84, v84, v84 quad_perm:[2,3,0,1] row_mask:0xf bank_mask:0xf bound_ctrl:1
	v_pk_fma_f32 v[94:95], v[36:37], v[62:63], v[94:95] op_sel_hi:[1,0,1]
	v_pk_mul_f32 v[88:89], v[122:123], v[72:73] op_sel:[0,1] op_sel_hi:[1,1]
	v_add_f32_dpp v84, v84, v84 row_ror:4 row_mask:0xf bank_mask:0xf bound_ctrl:1
	v_pk_fma_f32 v[94:95], v[38:39], v[62:63], v[94:95] op_sel:[0,1,0] op_sel_hi:[1,1,1]
	v_pk_mul_f32 v[90:91], v[122:123], v[74:75] op_sel_hi:[1,0]
	v_add_f32_dpp v84, v84, v84 row_ror:8 row_mask:0xf bank_mask:0xf bound_ctrl:1
	v_pk_mul_f32 v[92:93], v[122:123], v[74:75] op_sel:[0,1] op_sel_hi:[1,1]
	v_add_f32_dpp v96, v95, v94 quad_perm:[1,0,3,2] row_mask:0xf bank_mask:0xf bound_ctrl:1
	ds_read_b128 v[60:63], v97 offset:24576
	v_mov_b32_dpp v85, v84 quad_perm:[1,0,3,2] row_mask:0xf bank_mask:0xf
	ds_write_b32 v99, v96 offset:14336
	v_pk_fma_f32 v[86:87], v[84:85], v[68:69], v[86:87] op_sel_hi:[1,0,1]
	v_pk_fma_f32 v[88:89], v[84:85], v[68:69], v[88:89] op_sel:[0,1,0] op_sel_hi:[1,1,1]
	v_pk_fma_f32 v[90:91], v[84:85], v[70:71], v[90:91] op_sel_hi:[1,0,1]
	v_pk_fma_f32 v[92:93], v[84:85], v[70:71], v[92:93] op_sel:[0,1,0] op_sel_hi:[1,1,1]
	v_pk_fma_f32 v[32:33], v[32:33], v[76:77], v[86:87] op_sel_hi:[1,0,1]
	v_pk_fma_f32 v[34:35], v[34:35], v[76:77], v[88:89] op_sel:[0,1,0] op_sel_hi:[1,1,1]
	v_pk_fma_f32 v[36:37], v[36:37], v[78:79], v[90:91] op_sel_hi:[1,0,1]
	v_pk_fma_f32 v[38:39], v[38:39], v[78:79], v[92:93] op_sel:[0,1,0] op_sel_hi:[1,1,1]
	s_waitcnt lgkmcnt(8)
	v_pk_mul_f32 v[94:95], v[32:33], v[80:81] op_sel_hi:[1,0]
	s_nop 0
	v_pk_fma_f32 v[94:95], v[34:35], v[80:81], v[94:95] op_sel:[0,1,0] op_sel_hi:[1,1,1]
	s_nop 0
	v_pk_fma_f32 v[94:95], v[36:37], v[82:83], v[94:95] op_sel_hi:[1,0,1]
	s_nop 0
	v_pk_fma_f32 v[94:95], v[38:39], v[82:83], v[94:95] op_sel:[0,1,0] op_sel_hi:[1,1,1]
	s_nop 1
	v_add_f32_dpp v96, v95, v94 quad_perm:[1,0,3,2] row_mask:0xf bank_mask:0xf bound_ctrl:1
	ds_write_b32 v99, v96 offset:15360
	s_add_i32 s15, s15, 16
	v_add_u32_e32 v97, 0x6000, v97
	v_add_u32_e32 v98, 0x6000, v98
	v_add_u32_e32 v99, 0x4000, v99
	s_waitcnt lgkmcnt(0)
	s_barrier
	s_cmp_lt_i32 s15, s54
	s_cbranch_scc1 .Lsc_grp
	s_add_i32 s13, s13, 1
	s_cmp_lt_u32 s13, s3
	s_cbranch_scc1 .Lsc_chunk
	s_mov_b32 s13, 0
	s_lshl_b64 s[54:55], s[12:13], 14
	s_cmp_eq_u64 s[50:51], 0
	s_mov_b32 s15, 0x94b6000
	s_cselect_b32 s15, 0x9192000, s15
	s_add_u32 s54, s54, s15
	s_addc_u32 s55, s55, 0
	s_add_u32 s54, s54, s40
	s_addc_u32 s55, s55, s41
	v_cndmask_b32_e32 v104, v32, v33, vcc
	v_cndmask_b32_e32 v108, v33, v32, vcc
	v_cndmask_b32_e32 v105, v34, v35, vcc
	v_cndmask_b32_e32 v109, v35, v34, vcc
	v_cndmask_b32_e32 v106, v36, v37, vcc
	v_cndmask_b32_e32 v110, v37, v36, vcc
	v_cndmask_b32_e32 v107, v38, v39, vcc
	v_cndmask_b32_e32 v111, v39, v38, vcc
	s_nop 1
	global_store_dwordx4 v103, v[104:107], s[54:55]
	global_store_dwordx4 v103, v[108:111], s[54:55] offset:256
	s_mov_b64 s[54:55], 0
	s_barrier
